# layer-0 context-query attention tiles also deferred past the out-phase barrier (WGs 248-255), context out units on WGs 208-231, counter threshold 32
# speedup vs baseline: 1.0173x; 1.0034x over previous
.LBB0_666:
	s_or_b64 exec, exec, s[0:1]
	v_readlane_b32 s0, v255, 23
	v_readlane_b32 s1, v255, 24
	s_movk_i32 s8, 0x100
	s_and_b64 vcc, exec, s[0:1]
	s_waitcnt lgkmcnt(0)
	s_barrier
	s_cbranch_vccz .LBB0_690
	s_mov_b32 s0, 0
	v_writelane_b32 v255, s0, 60
	s_cmpk_eq_i32 s36, 0x100
	s_cbranch_scc1 .LBB0_689
.Lcx_attn_entry:
	v_mov_b32_e32 v0, v206
	v_mov_b32_e32 v1, 0
	v_and_b32_e32 v2, 63, v0
	v_cmp_gt_u32_e32 vcc, 32, v2
	v_mov_b32_e32 v0, 0
	s_and_saveexec_b64 s[0:1], vcc
	s_cbranch_execz .LBB0_669
	ds_read_b64 v[0:1], v129 offset:152
	v_lshlrev_b32_e32 v2, 2, v2
	s_waitcnt lgkmcnt(0)
	v_readfirstlane_b32 s2, v0
	v_readfirstlane_b32 s3, v1
	s_nop 4
	global_load_dword v1, v2, s[2:3]
	global_load_dword v3, v2, s[2:3] offset:128
	global_load_dword v0, v2, s[2:3] offset:256
	s_nop 0
	global_load_dword v2, v2, s[2:3] offset:384
	s_waitcnt vmcnt(0)
	v_pk_mul_f32 v[0:1], v[0:1], v[2:3]

.LBB0_689:
	v_readlane_b32 s0, v255, 60
	s_cmp_eq_u32 s0, 1
	s_cbranch_scc1 .Lcx_attn_done
	s_movk_i32 s8, 0x108
	s_cmpk_eq_i32 s36, 0x100
	s_cselect_b32 s8, 0x100, s8

.LBB0_1212:
	s_or_b64 exec, exec, s[0:1]
	s_waitcnt lgkmcnt(0)
	s_barrier
	v_readlane_b32 s0, v255, 25
	v_readlane_b32 s1, v255, 0
	s_cmp_lg_u32 s0, 0
	s_cbranch_scc1 .Lcx_mark7
	s_cmpk_lg_i32 s36, 0x100
	s_cbranch_scc1 .Lcx_mark7
	s_cmp_ge_u32 s1, 248
	s_cbranch_scc1 .Lcx_attn
	s_sub_i32 s1, s1, 208
	s_cmp_lt_u32 s1, 24
	s_cbranch_scc0 .Lcx_mark7
	s_lshr_b32 s2, s1, 3
	s_mulk_i32 s2, 0x108
	s_bfe_u32 s3, s1, 0x10002
	s_mulk_i32 s3, 0x84
	s_and_b32 s1, s1, 3
	s_add_i32 s2, s2, s3
	s_add_i32 s29, s2, s1
	s_movk_i32 s8, 0x108
	s_mov_b32 s52, 0x10800
	s_mov_b32 s53, 0x8100
	s_mov_b32 s59, 0x3195000
	v_cvt_f32_u32_e32 v0, s8
	v_readlane_b32 s0, v255, 25
	s_sub_i32 s4, 0, s8
	v_readlane_b32 s1, v255, 26
	v_rcp_iflag_f32_e32 v0, v0
	s_mov_b32 s2, s0
	s_lshl_b32 s48, s0, 8
	s_lshl_b32 s10, s0, 10
	v_mul_f32_e32 v0, 0x4f7ffffe, v0
	v_cvt_u32_f32_e32 v0, v0
	s_lshl_b32 s24, s0, 1
	s_lshl_b32 s0, s0, 9
	s_mov_b32 s1, s49
	v_readfirstlane_b32 s5, v0
	s_mul_i32 s4, s4, s5
	s_lshl_b32 s14, s2, 11
	s_lshl_b32 s25, s2, 3
	s_lshl_b32 s26, s2, 2
	s_lshl_b32 s27, s2, 12
	s_lshl_b32 s2, s2, 6
	s_mov_b32 s3, s49
	s_mul_hi_u32 s4, s5, s4
	s_mov_b32 s11, s49
	s_mov_b32 s15, s49
	s_add_i32 s28, s5, s4
	s_lshl_b64 s[16:17], s[2:3], 2
	s_lshl_b64 s[18:19], s[0:1], 2
	s_mov_b32 s9, 0
	s_mov_b64 s[100:101], 0
	s_branch .LBB0_694
.Lcx_attn:
	s_mov_b32 s0, 1
	v_writelane_b32 v255, s0, 60
	s_movk_i32 s59, 0x90
	s_branch .Lcx_attn_entry
.Lcx_attn_done:
	s_mov_b32 s0, 0
	v_writelane_b32 v255, s0, 60
	s_branch .Lcx_done

.Lcx_wait:
	global_load_dword v0, v129, s[4:5] sc1
	s_add_i32 s8, s8, 1
	s_waitcnt vmcnt(0)
	v_readfirstlane_b32 s7, v0
	s_cmp_ge_u32 s7, 32
	s_cbranch_scc1 .Lcx_go
	s_cmp_gt_u32 s8, 0x8000
	s_cbranch_scc1 .Lcx_go
	s_sleep 2
	s_branch .Lcx_wait
